# P2 rebalance: GLA state scan moved to blocks 128-255 and chunk-0 GLA units to blocks 0-7 (lightest attention load)
# baseline (speedup 1.0000x reference)
.LBB0_19:
	s_or_b64 exec, exec, s[0:1]
	s_add_u32 s4, s94, 0x32ac900
	s_addc_u32 s5, s95, 0
	s_add_u32 s6, s94, 0x532c900
	s_addc_u32 s7, s95, 0
	s_add_u32 s80, s94, 0x3080000
	s_addc_u32 s81, s95, 0
	s_add_u32 s78, s94, 0x3102000
	s_addc_u32 s79, s95, 0
	s_add_u32 s14, s94, 0x3206000
	s_addc_u32 s15, s95, 0
	s_add_u32 s0, s94, 0x32a8800
	s_addc_u32 s1, s95, 0
	v_writelane_b32 v251, s0, 42
	s_cmp_eq_u32 s2, 0
	v_mov_b32_e32 v0, 0x840
	v_writelane_b32 v251, s1, 43
	s_cselect_b64 s[0:1], -1, 0
	s_add_u32 s86, s94, 0x1080000
	s_addc_u32 s87, s95, 0
	s_cmpk_lt_i32 s2, 0x555
	v_writelane_b32 v251, s0, 44
	s_cselect_b64 s[26:27], -1, 0
	s_ashr_i32 s3, s2, 31
	v_writelane_b32 v251, s1, 45
	s_lshr_b32 s0, s3, 29
	s_add_i32 s0, s2, s0
	s_ashr_i32 s1, s0, 3
	s_and_b32 s0, s0, -8
	s_sub_i32 s8, s2, s0
	s_mul_i32 s0, s8, 0xaa
	s_add_i32 s13, s0, 5
	s_ashr_i32 s33, s96, 31
	s_cmp_eq_u32 s9, 15
	s_cselect_b64 s[16:17], -1, 0
	v_writelane_b32 v251, s16, 46
	s_cmp_eq_u32 s9, 14
	v_sub_co_u32_e32 v0, vcc, s2, v0
	v_writelane_b32 v251, s17, 47
	s_cselect_b64 s[16:17], -1, 0
	v_writelane_b32 v251, s16, 48
	s_cmp_eq_u32 s9, 13
	v_mov_b32_e32 v1, 0xd80
	v_writelane_b32 v251, s17, 49
	s_cselect_b64 s[16:17], -1, 0
	v_writelane_b32 v251, s16, 50
	s_cmp_eq_u32 s9, 12
	v_mov_b32_e32 v2, 0xe00
	v_writelane_b32 v251, s17, 51
	s_cselect_b64 s[16:17], -1, 0
	v_writelane_b32 v251, s16, 52
	s_cmp_eq_u32 s9, 11
	v_mov_b32_e32 v3, 0xe80
	v_writelane_b32 v251, s17, 53
	s_cselect_b64 s[16:17], -1, 0
	v_writelane_b32 v251, s16, 54
	s_cmp_eq_u32 s9, 10
	v_mov_b32_e32 v4, 0xf80
	v_writelane_b32 v251, s17, 55
	s_cselect_b64 s[16:17], -1, 0
	v_writelane_b32 v251, s16, 56
	s_cmp_eq_u32 s9, 9
	v_mov_b32_e32 v5, 0x1500
	v_writelane_b32 v251, s17, 57
	s_cselect_b64 s[16:17], -1, 0
	v_writelane_b32 v251, s16, 58
	s_cmp_eq_u32 s9, 8
	v_mov_b32_e32 v139, 0
	v_writelane_b32 v251, s17, 59
	s_cselect_b64 s[16:17], -1, 0
	v_writelane_b32 v251, s16, 60
	s_cmp_eq_u32 s9, 7
	v_mov_b32_e32 v176, 1
	v_writelane_b32 v251, s17, 61
	s_cselect_b64 s[16:17], -1, 0
	v_writelane_b32 v251, s16, 62
	s_cmp_eq_u32 s9, 6
	v_mov_b32_e32 v177, 0x358637bd
	v_writelane_b32 v251, s17, 63
	s_cselect_b64 s[16:17], -1, 0
	v_writelane_b32 v252, s16, 0
	s_cmp_eq_u32 s9, 5
	v_readlane_b32 s36, v251, 8
	v_writelane_b32 v252, s17, 1
	s_cselect_b64 s[16:17], -1, 0
	v_writelane_b32 v252, s16, 2
	s_cmp_eq_u32 s9, 4
	v_readlane_b32 s48, v251, 20
	v_writelane_b32 v252, s17, 3
	s_cselect_b64 s[16:17], -1, 0
	v_writelane_b32 v252, s16, 4
	s_cmp_eq_u32 s9, 3
	v_readlane_b32 s49, v251, 21
	v_writelane_b32 v252, s17, 5
	s_cselect_b64 s[16:17], -1, 0
	v_writelane_b32 v252, s16, 6
	s_cmp_eq_u32 s9, 2
	v_readlane_b32 s37, v251, 9
	v_writelane_b32 v252, s17, 7
	s_cselect_b64 s[16:17], -1, 0
	v_writelane_b32 v252, s16, 8
	s_cmp_eq_u32 s9, 1
	v_readlane_b32 s38, v251, 10
	v_writelane_b32 v252, s17, 9
	s_cselect_b64 s[16:17], -1, 0
	v_writelane_b32 v252, s16, 10
	s_cmp_eq_u32 s9, 0
	v_readlane_b32 s39, v251, 11
	v_writelane_b32 v252, s17, 11
	s_cselect_b64 s[16:17], -1, 0
	s_lshl_b32 s0, s10, 2
	s_getpc_b64 s[10:11]
	s_add_u32 s10, s10, g_bar@rel32@lo+5124
	s_addc_u32 s11, s11, g_bar@rel32@hi+5132
	v_writelane_b32 v252, s16, 12
	s_add_u32 s10, s10, s0
	s_addc_u32 s11, s11, 0
	v_writelane_b32 v252, s17, 13
	v_writelane_b32 v252, s10, 14
	v_readlane_b32 s40, v251, 12
	v_readlane_b32 s41, v251, 13
	v_writelane_b32 v252, s11, 15
	s_getpc_b64 s[10:11]
	s_add_u32 s10, s10, g_bar@rel32@lo+9220
	s_addc_u32 s11, s11, g_bar@rel32@hi+9228
	s_add_u32 s90, s10, s0
	s_addc_u32 s91, s11, 0
	s_cmp_lt_u32 s2, 16
	s_cselect_b64 s[10:11], -1, 0
	s_and_b32 s0, s2, 7
	v_writelane_b32 v252, s10, 16
	s_lshl_b32 s9, s0, 2
	s_lshr_b32 s0, s2, 3
	v_writelane_b32 v252, s11, 17
	s_add_u32 s10, s80, s9
	s_addc_u32 s11, s81, 0
	v_writelane_b32 v252, s10, 18
	s_mul_i32 s9, s2, 0x8200
	v_readlane_b32 s42, v251, 14
	v_writelane_b32 v252, s11, 19
	v_writelane_b32 v252, s14, 20
	s_add_u32 s10, s14, s9
	v_writelane_b32 v252, s15, 21
	s_addc_u32 s11, s15, 0
	s_lshl_b32 s14, s96, 3
	s_lshl_b32 s82, s2, 3
	s_lshl_b32 s84, s96, 4
	v_writelane_b32 v252, s10, 22
	s_cmpk_lt_i32 s2, 0x200
	v_readlane_b32 s43, v251, 15
	v_writelane_b32 v252, s11, 23
	s_cselect_b64 s[10:11], -1, 0
	s_add_u32 s24, s94, 0x3288000
	v_writelane_b32 v252, s10, 24
	s_addc_u32 s25, s95, 0
	s_cmpk_ge_i32 s96, 0x100
	s_cselect_b32 s9, 0xffffff80, 0
	s_add_i32 s9, s2, s9
	s_lshl_b32 s9, s9, 9
	v_writelane_b32 v252, s11, 25
	s_cmpk_lt_i32 s96, 0x88
	v_writelane_b32 v252, s9, 26
	s_cselect_b64 s[10:11], -1, 0
	s_and_b32 s9, s2, -8
	v_writelane_b32 v252, s10, 27
	s_cmpk_eq_i32 s9, 0x0
	v_readlane_b32 s44, v251, 16
	v_writelane_b32 v252, s11, 28
	s_cselect_b64 s[10:11], -1, 0
	s_mov_b32 s9, s2
	v_writelane_b32 v252, s10, 29
	s_lshr_b32 s9, s9, 2
	v_readlane_b32 s45, v251, 17
	v_writelane_b32 v252, s11, 30
	s_mul_i32 s10, s9, 0x2080
	s_and_b32 s9, s2, 3
	s_lshl_b32 s15, s9, 6
	v_writelane_b32 v252, s15, 31
	s_lshl_b32 s15, s9, 7
	s_add_u32 s16, s6, s15
	v_writelane_b32 v252, s15, 32
	s_addc_u32 s17, s7, 0
	v_writelane_b32 v252, s16, 33
	s_mov_b32 s11, s75
	v_readlane_b32 s46, v251, 18
	v_writelane_b32 v252, s17, 34
	v_writelane_b32 v252, s10, 35
	v_readlane_b32 s16, v251, 0
	v_readlane_b32 s20, v251, 4
	v_writelane_b32 v252, s11, 36
	s_lshl_b64 s[10:11], s[10:11], 6
	s_add_u32 s10, s78, s10
	s_addc_u32 s11, s79, s11
	v_writelane_b32 v252, s10, 37
	s_lshl_b32 s9, s9, 9
	s_add_u32 s9, s48, s9
	v_writelane_b32 v252, s11, 38
	v_writelane_b32 v252, s9, 39
	s_addc_u32 s9, s49, 0
	v_writelane_b32 v252, s9, 40
	s_not_b32 s9, s2
	s_add_u32 s72, s94, 0x1b00000
	s_addc_u32 s73, s95, 0
	s_cmpk_lt_i32 s2, 0x100
	v_writelane_b32 v252, s9, 41
	s_cselect_b64 s[10:11], -1, 0
	s_lshl_b32 s9, s8, 5
	s_add_u32 s28, s94, 0x532dd00
	s_addc_u32 s29, s95, 0
	s_add_u32 s30, s94, 0x1c00000
	s_addc_u32 s31, s95, 0
	s_add_u32 s34, s94, 0x532cd00
	s_addc_u32 s35, s95, 0
	s_add_u32 s52, s94, 0x1d00000
	v_writelane_b32 v252, s10, 42
	s_addc_u32 s53, s95, 0
	v_readlane_b32 s21, v251, 5
	v_writelane_b32 v252, s11, 43
	s_add_u32 s10, s94, 0x2f80000
	s_addc_u32 s11, s95, 0
	v_writelane_b32 v252, s10, 44
	s_cmp_lg_u64 s[20:21], 0
	v_readlane_b32 s18, v251, 2
	v_writelane_b32 v252, s11, 45
	s_cselect_b64 s[10:11], -1, 0
	v_writelane_b32 v252, s10, 46
	v_readlane_b32 s19, v251, 3
	s_cmpk_lt_i32 s2, 0x596
	v_writelane_b32 v252, s11, 47
	s_mul_i32 s10, s8, 0xb2
	v_readlane_b32 s17, v251, 1
	s_cselect_b64 s[18:19], -1, 0
	s_add_i32 s15, s10, 6
	v_writelane_b32 v252, s18, 48
	s_cmp_lg_u64 s[16:17], 0
	s_cselect_b64 s[10:11], -1, 0
	v_writelane_b32 v252, s19, 49
	v_writelane_b32 v252, s10, 50
	s_cmpk_lt_i32 s2, 0x17c0
	v_readlane_b32 s47, v251, 19
	v_writelane_b32 v252, s11, 51
	s_cselect_b64 s[10:11], -1, 0
	v_writelane_b32 v252, s10, 52
	s_cmpk_gt_i32 s2, 0x57f
	v_readlane_b32 s50, v251, 22
	v_writelane_b32 v252, s11, 53
	s_cselect_b64 s[10:11], -1, 0
	v_writelane_b32 v252, s10, 54
	v_readlane_b32 s51, v251, 23
	v_readlane_b32 s36, v251, 24
	v_writelane_b32 v252, s11, 55
	s_xor_b64 s[10:11], vcc, -1
	v_writelane_b32 v252, s10, 56
	v_sub_co_u32_e32 v1, vcc, s2, v1
	s_nop 0
	v_writelane_b32 v252, s11, 57
	s_xor_b64 s[10:11], vcc, -1
	v_writelane_b32 v252, s10, 58
	v_sub_co_u32_e32 v2, vcc, s2, v2
	s_nop 0
	v_writelane_b32 v252, s11, 59
	s_xor_b64 s[10:11], vcc, -1
	v_writelane_b32 v252, s10, 60
	v_sub_co_u32_e32 v3, vcc, s2, v3
	s_nop 0
	v_writelane_b32 v252, s11, 61
	s_xor_b64 s[10:11], vcc, -1
	v_writelane_b32 v252, s10, 62
	v_sub_co_u32_e32 v4, vcc, s2, v4
	s_nop 0
	v_writelane_b32 v252, s11, 63
	s_xor_b64 s[10:11], vcc, -1
	v_writelane_b32 v250, s10, 0
	v_sub_co_u32_e32 v5, vcc, s2, v5
	s_nop 0
	v_writelane_b32 v250, s11, 1
	s_xor_b64 s[10:11], vcc, -1
	v_writelane_b32 v250, s10, 2
	v_readlane_b32 s48, v251, 36
	v_readlane_b32 s49, v251, 37
	v_writelane_b32 v250, s11, 3
	s_add_u32 s10, s94, 0x2a00000
	s_addc_u32 s11, s95, 0
	v_writelane_b32 v250, s10, 4
	v_readlane_b32 s22, v251, 6
	v_readlane_b32 s23, v251, 7
	v_writelane_b32 v250, s11, 5
	s_add_u32 s10, s94, 0x1f00000
	s_addc_u32 s11, s95, 0
	v_writelane_b32 v250, s10, 6
	v_readlane_b32 s37, v251, 25
	v_readlane_b32 s38, v251, 26
	v_writelane_b32 v250, s11, 7
	s_add_u32 s10, s94, 0xb00000
	s_addc_u32 s11, s95, 0
	v_writelane_b32 v250, s10, 8
	v_readlane_b32 s39, v251, 27
	v_mov_b32_e32 v178, 3
	v_writelane_b32 v250, s11, 9
	s_add_i32 s10, s2, 0xfffffa80
	s_cmp_lg_u64 s[48:49], 0
	v_writelane_b32 v250, s10, 10
	s_cselect_b64 s[54:55], -1, 0
	s_cmp_lt_i32 s8, 5
	s_mul_i32 s10, s8, 0xab
	s_cselect_b32 s10, s10, s13
	s_add_i32 s10, s10, s1
	s_mul_hi_i32 s11, s10, 0x30c30c31
	s_lshr_b32 s13, s11, 31
	s_ashr_i32 s11, s11, 4
	s_add_i32 s11, s11, s13
	s_mul_i32 s13, s11, 0x54
	s_lshl_b32 s18, s11, 2
	s_sub_i32 s13, s10, s13
	s_sub_i32 s10, 0x41, s18
	s_min_u32 s19, s10, 4
	s_cmp_lt_i32 s8, 0
	s_mul_i32 s10, s8, 33
	s_cselect_b32 s9, s10, s9
	s_add_i32 s9, s9, s1
	s_ashr_i32 s10, s9, 31
	s_lshr_b32 s10, s10, 28
	s_add_i32 s10, s9, s10
	s_and_b32 s11, s10, 0xfff0
	s_sub_i32 s9, s9, s11
	s_bfe_i32 s11, s9, 0x80000
	s_bfe_u32 s11, s11, 0x2000d
	s_add_i32 s11, s9, s11
	s_and_b32 s16, s11, 0xfc
	s_sub_i32 s9, s9, s16
	s_ashr_i32 s10, s10, 4
	s_lshl_b32 s10, s10, 2
	s_sext_i32_i8 s9, s9
	s_add_i32 s21, s10, s9
	s_bfe_i32 s9, s11, 0x80000
	s_sext_i32_i16 s9, s9
	s_ashr_i32 s10, s9, 2
	v_writelane_b32 v250, s10, 11
	s_lshr_b32 s10, s9, 2
	s_bfe_i64 s[10:11], s[10:11], 0x100000
	s_lshl_b64 s[16:17], s[10:11], 18
	s_add_u32 s22, s72, s16
	s_addc_u32 s23, s73, s17
	s_add_u32 s36, s22, 0x20000
	s_addc_u32 s37, s23, 0
	v_writelane_b32 v250, s36, 12
	s_mul_i32 s20, s21, 0x280000
	s_mul_hi_i32 s9, s21, 0x280000
	v_writelane_b32 v250, s37, 13
	s_add_u32 s36, s6, s20
	s_addc_u32 s37, s7, s9
	s_add_u32 s38, s36, 0x140000
	v_writelane_b32 v250, s36, 14
	s_addc_u32 s39, s37, 0
	v_cvt_f32_ubyte0_e32 v7, s19
	v_writelane_b32 v250, s37, 15
	v_writelane_b32 v250, s38, 16
	s_add_u32 s36, s22, 0x20080
	v_cvt_f32_i32_e32 v6, s13
	v_writelane_b32 v250, s39, 17
	v_writelane_b32 v250, s22, 18
	s_addc_u32 s37, s23, 0
	s_add_u32 s16, s30, s16
	v_writelane_b32 v250, s23, 19
	v_writelane_b32 v250, s36, 20
	v_rcp_iflag_f32_e32 v8, v7
	v_mov_b32_e32 v179, 0x260
	v_writelane_b32 v250, s37, 21
	v_writelane_b32 v250, s30, 22
	s_addc_u32 s17, s31, s17
	s_add_u32 s22, s16, 0x20000
	v_writelane_b32 v250, s31, 23
	s_addc_u32 s23, s17, 0
	v_writelane_b32 v250, s22, 24
	v_mul_f32_e32 v8, v6, v8
	v_trunc_f32_e32 v8, v8
	v_writelane_b32 v250, s23, 25
	s_add_u32 s22, s28, s20
	v_writelane_b32 v250, s28, 26
	s_addc_u32 s23, s29, s9
	v_fma_f32 v6, -v8, v7, v6
	v_writelane_b32 v250, s29, 27
	s_add_u32 s28, s22, 0x140000
	v_writelane_b32 v250, s22, 28
	s_addc_u32 s29, s23, 0
	v_mov_b64_e32 v[140:141], 0x555
	v_writelane_b32 v250, s23, 29
	v_writelane_b32 v250, s28, 30
	s_add_u32 s22, s16, 0x20080
	v_mov_b64_e32 v[142:143], 0x554
	v_writelane_b32 v250, s29, 31
	v_writelane_b32 v250, s16, 32
	s_addc_u32 s23, s17, 0
	s_lshl_b64 s[10:11], s[10:11], 19
	v_writelane_b32 v250, s17, 33
	v_writelane_b32 v250, s22, 34
	s_add_u32 s10, s52, s10
	v_mov_b32_e32 v180, 0x41b17218
	v_writelane_b32 v250, s23, 35
	v_writelane_b32 v250, s52, 36
	s_addc_u32 s11, s53, s11
	s_add_u32 s16, s10, 0x40000
	v_writelane_b32 v250, s53, 37
	s_addc_u32 s17, s11, 0
	v_writelane_b32 v250, s16, 38
	v_mov_b32_e32 v181, 0x3e000000
	v_mov_b32_e32 v182, 0x3e38aa3b
	v_writelane_b32 v250, s17, 39
	s_add_u32 s16, s34, s20
	v_writelane_b32 v250, s34, 40
	s_addc_u32 s17, s35, s9
	s_add_u32 s22, s16, 0x140000
	v_writelane_b32 v250, s35, 41
	v_writelane_b32 v250, s16, 42
	s_addc_u32 s23, s17, 0
	v_mov_b32_e32 v184, 0x2800
	v_writelane_b32 v250, s17, 43
	v_writelane_b32 v250, s22, 44
	s_add_u32 s16, s10, 0x40080
	v_mov_b32_e32 v185, 0x7f800000
	v_writelane_b32 v250, s23, 45
	v_writelane_b32 v250, s10, 46
	s_addc_u32 s17, s11, 0
	s_cmp_lt_i32 s8, 6
	s_mulk_i32 s8, 0xb3
	s_cselect_b32 s8, s8, s15
	s_add_i32 s8, s8, s1
	s_mul_hi_i32 s1, s8, 0x2e8ba2e9
	s_lshr_b32 s9, s1, 31
	s_ashr_i32 s1, s1, 4
	s_add_i32 s1, s1, s9
	v_writelane_b32 v250, s11, 47
	s_lshl_b32 s11, s1, 2
	s_mul_i32 s9, s1, 0x58
	s_sub_i32 s1, 0x41, s11
	s_sub_i32 s10, s8, s9
	s_min_u32 s15, s1, 4
	s_mul_i32 s8, s21, 0x160000
	v_writelane_b32 v250, s16, 48
	s_mul_hi_i32 s1, s21, 0x160000
	s_add_u32 s8, s6, s8
	v_writelane_b32 v250, s17, 49
	s_addc_u32 s9, s7, s1
	s_add_u32 s16, s8, 0xb0000
	v_writelane_b32 v250, s8, 50
	s_addc_u32 s17, s9, 0
	s_ashr_i32 s1, s13, 30
	v_writelane_b32 v250, s9, 51
	v_cmp_ge_f32_e64 s[8:9], |v6|, v7
	v_cvt_i32_f32_e32 v6, v8
	s_or_b32 s1, s1, 1
	s_and_b64 s[8:9], s[8:9], exec
	v_writelane_b32 v250, s16, 52
	s_cselect_b32 s1, s1, 0
	v_readfirstlane_b32 s8, v6
	v_writelane_b32 v250, s17, 53
	s_add_i32 s16, s8, s1
	s_mul_i32 s1, s16, s19
	s_sub_i32 s1, s13, s1
	s_sext_i32_i8 s1, s1
	s_add_i32 s1, s18, s1
	v_writelane_b32 v250, s1, 54
	s_mul_i32 s1, s0, 0x2080
	s_ashr_i32 s0, s10, 30
	s_or_b32 s8, s0, 1
	s_or_b32 s0, s1, 1
	v_writelane_b32 v250, s0, 55
	s_or_b32 s0, s1, 2
	v_writelane_b32 v250, s0, 56
	s_or_b32 s0, s1, 3
	v_writelane_b32 v250, s0, 57
	s_or_b32 s0, s1, 4
	v_writelane_b32 v250, s0, 58
	s_or_b32 s0, s1, 5
	v_writelane_b32 v250, s0, 59
	s_or_b32 s0, s1, 6
	v_writelane_b32 v250, s0, 60
	s_or_b32 s0, s1, 7
	v_writelane_b32 v250, s0, 61
	s_or_b32 s0, s1, 8
	v_writelane_b32 v250, s0, 62
	s_or_b32 s0, s1, 9
	v_cvt_f32_ubyte0_e32 v7, s15
	v_writelane_b32 v250, s0, 63
	s_or_b32 s0, s1, 10
	v_cvt_f32_i32_e32 v6, s10
	v_rcp_iflag_f32_e32 v8, v7
	v_writelane_b32 v249, s0, 0
	s_or_b32 s0, s1, 11
	v_writelane_b32 v249, s0, 1
	s_or_b32 s0, s1, 12
	v_writelane_b32 v249, s0, 2
	s_or_b32 s0, s1, 13
	v_writelane_b32 v249, s0, 3
	s_or_b32 s0, s1, 14
	v_mul_f32_e32 v8, v6, v8
	v_writelane_b32 v249, s0, 4
	s_or_b32 s0, s1, 15
	v_trunc_f32_e32 v8, v8
	v_writelane_b32 v249, s0, 5
	v_fma_f32 v6, -v8, v7, v6
	v_writelane_b32 v249, s1, 6
	s_or_b32 s0, s1, 16
	v_writelane_b32 v249, s0, 7
	v_cmp_ge_f32_e64 s[0:1], |v6|, v7
	v_cvt_i32_f32_e32 v6, v8
	s_and_b64 s[0:1], s[0:1], exec
	s_cselect_b32 s0, s8, 0
	v_mov_b32_e32 v186, 0xff800000
	v_readfirstlane_b32 s1, v6
	s_add_i32 s0, s1, s0
	s_mul_i32 s1, s0, s15
	s_sub_i32 s1, s10, s1
	s_sext_i32_i8 s1, s1
	s_bfe_i64 s[8:9], s[0:1], 0x80000
	s_lshl_b64 s[8:9], s[8:9], 19
	s_add_i32 s10, s11, s1
	v_writelane_b32 v249, s8, 8
	s_ashr_i32 s11, s10, 31
	s_sext_i32_i8 s0, s0
	v_writelane_b32 v249, s9, 9
	s_mov_b32 s8, s10
	v_writelane_b32 v249, s8, 10
	s_mul_i32 s1, s97, s96
	s_mul_i32 s74, s1, s12
	v_writelane_b32 v249, s9, 11
	v_writelane_b32 v249, s26, 12
	s_lshl_b64 s[8:9], s[10:11], 19
	s_add_u32 s8, s4, s8
	v_writelane_b32 v249, s27, 13
	v_writelane_b32 v249, s0, 14
	s_sext_i32_i8 s0, s16
	s_addc_u32 s9, s5, s9
	v_writelane_b32 v249, s0, 15
	s_add_u32 s0, s8, 0x40000
	v_writelane_b32 v249, s8, 16
	s_addc_u32 s1, s9, 0
	s_ashr_i32 s85, s84, 31
	v_writelane_b32 v249, s9, 17
	v_writelane_b32 v249, s0, 18
	v_cndmask_b32_e64 v137, 0, 1, s[26:27]
	v_mbcnt_lo_u32_b32 v6, -1, 0
	v_writelane_b32 v249, s1, 19
	v_readfirstlane_b32 s0, v0
	v_mbcnt_hi_u32_b32 v183, -1, v6
	v_mov_b64_e32 v[144:145], 0x100
	v_writelane_b32 v249, s0, 20
	v_readfirstlane_b32 s0, v1
	v_mov_b64_e32 v[146:147], 0xff
	v_mov_b32_e32 v187, 0xffffdf80
	v_writelane_b32 v249, s0, 21
	v_readfirstlane_b32 s0, v2
	v_mov_b32_e32 v188, 0x2000
	v_mov_b32_e32 v189, 0x80
	v_writelane_b32 v249, s0, 22
	v_readfirstlane_b32 s0, v3
	v_mov_b64_e32 v[148:149], 0x596
	v_mov_b64_e32 v[150:151], 0x595
	v_writelane_b32 v249, s0, 23
	v_readfirstlane_b32 s0, v4
	s_movk_i32 s77, 0x80
	s_lshl_b32 s15, s96, 5
	v_writelane_b32 v249, s0, 24
	v_readfirstlane_b32 s0, v5
	s_movk_i32 s8, 0x2000
	s_mov_b32 s88, 0x14000
	v_writelane_b32 v249, s0, 25
	s_lshl_b32 s0, s96, 6
	v_writelane_b32 v249, s0, 26
	s_lshl_b32 s0, s2, 5
	v_writelane_b32 v249, s0, 27
	s_add_i32 s0, 0, 0x20000
	v_writelane_b32 v249, s0, 28
	s_add_i32 s0, 0, 0x20004
	v_writelane_b32 v249, s0, 29
	s_add_i32 s0, 0, 0x11000
	v_writelane_b32 v249, s0, 30
	s_add_i32 s0, 0, 0x19800
	v_writelane_b32 v249, s0, 31
	s_add_i32 s0, 0, 0x1c820
	v_writelane_b32 v249, s0, 32
	s_add_i32 s0, 0, 0x1c810
	v_writelane_b32 v249, s0, 33
	s_lshl_b64 s[0:1], s[84:85], 11
	v_writelane_b32 v249, s0, 34
	s_mov_b32 s85, s21
	s_movk_i32 s9, 0x207f
	v_writelane_b32 v249, s1, 35
	v_writelane_b32 v249, s54, 36
	s_movk_i32 s69, 0x6f
	s_mov_b32 s31, 0xbfb8aa3b
	v_writelane_b32 v249, s55, 37
	v_writelane_b32 v249, s84, 38
	s_mov_b32 s28, 0x800000
	s_mov_b32 s29, 0x3f317217
	v_writelane_b32 v249, s85, 39
	v_writelane_b32 v249, s72, 40
	s_mov_b32 s30, 0x7f800000
	s_movk_i32 s22, 0x2800
	v_writelane_b32 v249, s73, 41
	v_writelane_b32 v249, s85, 42
	s_movk_i32 s23, 0x4100
	s_movk_i32 s97, 0x1000
	s_movk_i32 s10, 0x110
	s_mov_b32 s11, 0xff800000
	s_movk_i32 s76, 0x1600
	s_movk_i32 s83, 0x5ff
	s_mov_b64 s[16:17], 0x80
	s_mov_b32 s52, s75
	v_writelane_b32 v249, s74, 43
	v_readlane_b32 s40, v251, 28
	v_readlane_b32 s41, v251, 29
	v_readlane_b32 s42, v251, 30
	v_readlane_b32 s43, v251, 31
	v_readlane_b32 s44, v251, 32
	v_readlane_b32 s45, v251, 33
	v_readlane_b32 s46, v251, 34
	v_readlane_b32 s47, v251, 35
	v_readlane_b32 s50, v251, 38
	v_readlane_b32 s51, v251, 39
	v_writelane_b32 v249, s82, 44
	s_branch .LBB0_23

.LBB0_552:
	s_or_b64 exec, exec, s[12:13]
	s_waitcnt lgkmcnt(0)
	v_mov_b32_e32 v0, v136
	v_readlane_b32 s0, v252, 26
	s_barrier
	s_nop 0
	v_add_u32_e32 v1, s0, v0
	s_mov_b32 s0, 0x10000
	v_cmp_gt_u32_e32 vcc, s0, v1
	s_and_saveexec_b64 s[12:13], vcc
	s_cbranch_execz .LBB0_559
	v_ashrrev_i32_e32 v28, 13, v1
	v_and_b32_e32 v1, 0x1fff, v1
	v_and_b32_e32 v31, 63, v0
	v_mul_i32_i24_e32 v0, 0x41, v28
	v_lshlrev_b32_e32 v138, 2, v1
	v_ashrrev_i32_e32 v1, 31, v0
	v_lshl_add_u64 v[2:3], s[4:5], 0, v[138:139]
	v_lshlrev_b64 v[4:5], 15, v[0:1]
	v_lshl_add_u64 v[4:5], v[2:3], 0, v[4:5]
	global_load_dword v1, v[4:5], off
	v_mul_i32_i24_e32 v4, 0x1040, v28
	v_or_b32_e32 v4, v4, v31
	v_ashrrev_i32_e32 v5, 31, v4
	v_lshl_add_u64 v[4:5], v[4:5], 2, s[24:25]
	s_movk_i32 s0, 0x41
	global_load_dword v10, v[4:5], off
	v_mad_i32_i24 v4, v28, s0, 1
	v_ashrrev_i32_e32 v5, 31, v4
	v_lshlrev_b64 v[6:7], 15, v[4:5]
	v_lshl_or_b32 v4, v4, 6, v31
	v_ashrrev_i32_e32 v5, 31, v4
	v_lshl_add_u64 v[6:7], v[2:3], 0, v[6:7]
	v_lshl_add_u64 v[4:5], v[4:5], 2, s[24:25]
	global_load_dword v8, v[6:7], off
	global_load_dword v12, v[4:5], off
	v_mad_i32_i24 v4, v28, s0, 2
	v_ashrrev_i32_e32 v5, 31, v4
	v_lshlrev_b64 v[6:7], 15, v[4:5]
	v_lshl_or_b32 v4, v4, 6, v31
	v_ashrrev_i32_e32 v5, 31, v4
	v_lshl_add_u64 v[6:7], v[2:3], 0, v[6:7]
	v_lshl_add_u64 v[4:5], v[4:5], 2, s[24:25]
	global_load_dword v9, v[6:7], off
	global_load_dword v13, v[4:5], off
	v_mad_i32_i24 v4, v28, s0, 3
	v_ashrrev_i32_e32 v5, 31, v4
	v_lshlrev_b64 v[6:7], 15, v[4:5]
	v_lshl_or_b32 v4, v4, 6, v31
	v_ashrrev_i32_e32 v5, 31, v4
	v_lshl_add_u64 v[6:7], v[2:3], 0, v[6:7]
	v_lshl_add_u64 v[4:5], v[4:5], 2, s[24:25]
	global_load_dword v11, v[6:7], off
	global_load_dword v17, v[4:5], off
	v_mad_i32_i24 v4, v28, s0, 4
	v_ashrrev_i32_e32 v5, 31, v4
	v_lshlrev_b64 v[6:7], 15, v[4:5]
	v_lshl_or_b32 v4, v4, 6, v31
	v_ashrrev_i32_e32 v5, 31, v4
	v_lshl_add_u64 v[6:7], v[2:3], 0, v[6:7]
	v_lshl_add_u64 v[4:5], v[4:5], 2, s[24:25]
	global_load_dword v14, v[6:7], off
	global_load_dword v18, v[4:5], off
	v_mad_i32_i24 v4, v28, s0, 5
	v_ashrrev_i32_e32 v5, 31, v4
	v_lshlrev_b64 v[6:7], 15, v[4:5]
	v_lshl_or_b32 v4, v4, 6, v31
	v_ashrrev_i32_e32 v5, 31, v4
	v_lshl_add_u64 v[6:7], v[2:3], 0, v[6:7]
	v_lshl_add_u64 v[4:5], v[4:5], 2, s[24:25]
	global_load_dword v15, v[6:7], off
	global_load_dword v20, v[4:5], off
	v_mad_i32_i24 v4, v28, s0, 6
	v_ashrrev_i32_e32 v5, 31, v4
	v_lshlrev_b64 v[6:7], 15, v[4:5]
	v_lshl_or_b32 v4, v4, 6, v31
	v_ashrrev_i32_e32 v5, 31, v4
	v_lshl_add_u64 v[6:7], v[2:3], 0, v[6:7]
	v_lshl_add_u64 v[4:5], v[4:5], 2, s[24:25]
	global_load_dword v16, v[6:7], off
	global_load_dword v21, v[4:5], off
	v_mad_i32_i24 v4, v28, s0, 7
	v_ashrrev_i32_e32 v5, 31, v4
	v_lshlrev_b64 v[6:7], 15, v[4:5]
	v_lshl_or_b32 v4, v4, 6, v31
	v_ashrrev_i32_e32 v5, 31, v4
	v_lshl_add_u64 v[6:7], v[2:3], 0, v[6:7]
	v_lshl_add_u64 v[4:5], v[4:5], 2, s[24:25]
	global_load_dword v19, v[6:7], off
	global_load_dword v25, v[4:5], off
	v_mad_i32_i24 v4, v28, s0, 8
	v_ashrrev_i32_e32 v5, 31, v4
	v_lshlrev_b64 v[6:7], 15, v[4:5]
	v_lshl_or_b32 v4, v4, 6, v31
	v_ashrrev_i32_e32 v5, 31, v4
	v_lshl_add_u64 v[6:7], v[2:3], 0, v[6:7]
	v_lshl_add_u64 v[4:5], v[4:5], 2, s[24:25]
	global_load_dword v22, v[6:7], off
	global_load_dword v26, v[4:5], off
	v_mad_i32_i24 v4, v28, s0, 9
	v_ashrrev_i32_e32 v5, 31, v4
	v_lshlrev_b64 v[6:7], 15, v[4:5]
	v_lshl_or_b32 v4, v4, 6, v31
	v_ashrrev_i32_e32 v5, 31, v4
	v_lshl_add_u64 v[6:7], v[2:3], 0, v[6:7]
	v_lshl_add_u64 v[4:5], v[4:5], 2, s[24:25]
	global_load_dword v23, v[6:7], off
	global_load_dword v29, v[4:5], off
	v_mad_i32_i24 v4, v28, s0, 10
	v_ashrrev_i32_e32 v5, 31, v4
	v_lshlrev_b64 v[6:7], 15, v[4:5]
	v_lshl_or_b32 v4, v4, 6, v31
	v_ashrrev_i32_e32 v5, 31, v4
	v_lshl_add_u64 v[6:7], v[2:3], 0, v[6:7]
	v_lshl_add_u64 v[4:5], v[4:5], 2, s[24:25]
	global_load_dword v24, v[6:7], off
	global_load_dword v30, v[4:5], off
	v_mad_i32_i24 v4, v28, s0, 11
	v_ashrrev_i32_e32 v5, 31, v4
	v_lshlrev_b64 v[6:7], 15, v[4:5]
	v_lshl_or_b32 v4, v4, 6, v31
	v_ashrrev_i32_e32 v5, 31, v4
	v_lshl_add_u64 v[6:7], v[2:3], 0, v[6:7]
	v_lshl_add_u64 v[4:5], v[4:5], 2, s[24:25]
	global_load_dword v27, v[6:7], off
	global_load_dword v33, v[4:5], off
	v_mad_i32_i24 v4, v28, s0, 12
	v_ashrrev_i32_e32 v5, 31, v4
	v_lshlrev_b64 v[6:7], 15, v[4:5]
	v_lshl_or_b32 v4, v4, 6, v31
	v_ashrrev_i32_e32 v5, 31, v4
	v_lshl_add_u64 v[6:7], v[2:3], 0, v[6:7]
	v_lshl_add_u64 v[4:5], v[4:5], 2, s[24:25]
	global_load_dword v28, v[6:7], off
	global_load_dword v34, v[4:5], off
	v_lshl_or_b32 v4, v0, 6, v31
	v_add_u32_e32 v4, 0x340, v4
	s_mov_b32 s26, 0
	v_mov_b32_e32 v43, 0
	s_branch .LBB0_555
